# FFN-up epilogue: relu^2 f16 results restaged in place through the LDS C tile, contiguous 1 KiB wave stores into the blocked hidden layout
# speedup vs baseline: 1.0631x; 1.0163x over previous
; DI unsigned pack2(float a, float b) { f32x2 v = {a, b}; bfx2 r = __builtin_convertvector(v, bfx2); return __builtin_bit_cast(unsigned, r); }
; DI size_t hid_off(int m, int c) { const int ml = m & 4095; return (size_t)(m >> 12) * (SLAB / 2) + ((size_t)((ml >> 8) * 128 + (c >> 5)) << 13) + (size_t)((ml & 255) * 32 + (c & 31)); }
; template <int MODE, bool BIG = false> DI void gemm_tile(const Params& p, int tm, int tn, int kv, char* smem) {
;     ...
;   } else if constexpr (MODE == G_FF1) {
;     u16* hid = (u16*)(p.ws + OFF_PROJ);
; #pragma unroll
;     for (int c8 = 0; c8 < 8; ++c8) {
;       float4 v0 = crow4[2 * c8], v1 = crow4[2 * c8 + 1];
;       float v[8] = {v0.x, v0.y, v0.z, v0.w, v1.x, v1.y, v1.z, v1.w};
; #pragma unroll
;       for (int e = 0; e < 8; ++e) { float t = fmaxf(v[e], 0.f); v[e] = t * t; }
;       *(uint4*)(hid + hid_off(m, col0 + c8 * 8)) = make_uint4(pack2(v[0], v[1]), pack2(v[2], v[3]), pack2(v[4], v[5]), pack2(v[6], v[7]));
;     }
.LBB0_980:
	s_or_b64 exec, exec, s[6:7]
	v_lshl_add_u32 v152, s15, 7, v130
	v_lshrrev_b32_e32 v134, 1, v152
	s_waitcnt lgkmcnt(0)
	s_barrier
	v_and_b32_e32 v156, 0x780, v134
	ds_read_b128 v[134:137], v129
	v_ashrrev_i32_e32 v140, 12, v152
	v_mov_b64_e32 v[138:139], s[58:59]
	v_mad_i64_i32 v[150:151], s[6:7], v140, s11, v[138:139]
	ds_read_b128 v[138:141], v129 offset:16
	ds_read_b128 v[142:145], v129 offset:32
	ds_read_b128 v[146:149], v129 offset:48
	s_waitcnt lgkmcnt(3)
	v_max_f32_e32 v134, v134, v134
	v_max_f32_e32 v135, v135, v135
	v_max_f32_e32 v136, v136, v136
	v_max_f32_e32 v137, v137, v137
	s_waitcnt lgkmcnt(2)
	v_max_f32_e32 v138, v138, v138
	v_max_f32_e32 v139, v139, v139
	v_max_f32_e32 v134, 0, v134
	v_max_f32_e32 v135, 0, v135
	v_max_f32_e32 v136, 0, v136
	v_max_f32_e32 v137, 0, v137
	v_max_f32_e32 v138, 0, v138
	v_max_f32_e32 v139, 0, v139
	v_pk_mul_f32 v[134:135], v[134:135], v[134:135]
	v_pk_mul_f32 v[136:137], v[136:137], v[136:137]
	v_pk_mul_f32 v[138:139], v[138:139], v[138:139]
	v_max_f32_e32 v140, v140, v140
	v_max_f32_e32 v141, v141, v141
	v_max_f32_e32 v140, 0, v140
	v_max_f32_e32 v141, 0, v141
	v_cvt_pk_f16_f32 v134, v134, v135
	v_cvt_pk_f16_f32 v135, v136, v137
	v_cvt_pk_f16_f32 v136, v138, v139
	v_add_u32_e32 v138, v156, v132
	v_pk_mul_f32 v[140:141], v[140:141], v[140:141]
	v_ashrrev_i32_e32 v139, 31, v138
	v_cvt_pk_f16_f32 v137, v140, v141
	v_lshlrev_b64 v[138:139], 14, v[138:139]
	v_lshlrev_b32_e32 v140, 6, v152
	v_lshl_add_u64 v[138:139], v[150:151], 0, v[138:139]
	v_and_b32_e32 v152, 0x3fc0, v140
	v_lshl_add_u64 v[154:155], v[138:139], 0, v[152:153]
	s_waitcnt lgkmcnt(0)
	v_max_f32_e32 v138, v146, v146
	v_max_f32_e32 v139, v147, v147
	v_max_f32_e32 v138, 0, v138
	v_max_f32_e32 v139, 0, v139
	ds_write_b128 v129, v[134:137]
	s_xor_b64 s[2:3], s[2:3], -1
	s_mov_b32 s15, 1
	v_max_f32_e32 v134, v142, v142
	v_max_f32_e32 v135, v143, v143
	v_max_f32_e32 v136, v144, v144
	v_max_f32_e32 v137, v145, v145
	v_pk_mul_f32 v[142:143], v[138:139], v[138:139]
	v_max_f32_e32 v138, v148, v148
	v_max_f32_e32 v139, v149, v149
	v_max_f32_e32 v134, 0, v134
	v_max_f32_e32 v135, 0, v135
	v_max_f32_e32 v136, 0, v136
	v_max_f32_e32 v137, 0, v137
	v_max_f32_e32 v138, 0, v138
	v_max_f32_e32 v139, 0, v139
	v_pk_mul_f32 v[134:135], v[134:135], v[134:135]
	v_pk_mul_f32 v[136:137], v[136:137], v[136:137]
	v_pk_mul_f32 v[144:145], v[138:139], v[138:139]
	v_cvt_pk_f16_f32 v134, v134, v135
	v_cvt_pk_f16_f32 v135, v136, v137
	v_cvt_pk_f16_f32 v136, v142, v143
	v_cvt_pk_f16_f32 v137, v144, v145
	ds_read_b128 v[138:141], v129 offset:64
	ds_write_b128 v129, v[134:137] offset:16
	ds_read_b128 v[134:137], v129 offset:80
	s_andn2_b64 vcc, exec, s[2:3]
	s_mov_b64 s[2:3], 0
	s_waitcnt lgkmcnt(1)
	v_max_f32_e32 v138, v138, v138
	v_max_f32_e32 v139, v139, v139
	s_waitcnt lgkmcnt(0)
	v_max_f32_e32 v134, v134, v134
	v_max_f32_e32 v135, v135, v135
	v_max_f32_e32 v134, 0, v134
	v_max_f32_e32 v135, 0, v135
	v_max_f32_e32 v140, v140, v140
	v_max_f32_e32 v141, v141, v141
	v_pk_mul_f32 v[142:143], v[134:135], v[134:135]
	v_max_f32_e32 v134, v136, v136
	v_max_f32_e32 v135, v137, v137
	v_max_f32_e32 v138, 0, v138
	v_max_f32_e32 v139, 0, v139
	v_max_f32_e32 v140, 0, v140
	v_max_f32_e32 v141, 0, v141
	v_max_f32_e32 v134, 0, v134
	v_max_f32_e32 v135, 0, v135
	v_pk_mul_f32 v[138:139], v[138:139], v[138:139]
	v_pk_mul_f32 v[140:141], v[140:141], v[140:141]
	v_pk_mul_f32 v[144:145], v[134:135], v[134:135]
	v_cvt_pk_f16_f32 v134, v138, v139
	v_cvt_pk_f16_f32 v135, v140, v141
	v_cvt_pk_f16_f32 v136, v142, v143
	v_cvt_pk_f16_f32 v137, v144, v145
	ds_read_b128 v[138:141], v129 offset:96
	ds_write_b128 v129, v[134:137] offset:32
	ds_read_b128 v[134:137], v129 offset:112
	s_waitcnt lgkmcnt(1)
	v_max_f32_e32 v138, v138, v138
	v_max_f32_e32 v139, v139, v139
	s_waitcnt lgkmcnt(0)
	v_max_f32_e32 v134, v134, v134
	v_max_f32_e32 v135, v135, v135
	v_max_f32_e32 v134, 0, v134
	v_max_f32_e32 v135, 0, v135
	v_max_f32_e32 v140, v140, v140
	v_max_f32_e32 v141, v141, v141
	v_pk_mul_f32 v[142:143], v[134:135], v[134:135]
	v_max_f32_e32 v134, v136, v136
	v_max_f32_e32 v135, v137, v137
	v_max_f32_e32 v138, 0, v138
	v_max_f32_e32 v139, 0, v139
	v_max_f32_e32 v140, 0, v140
	v_max_f32_e32 v141, 0, v141
	v_max_f32_e32 v134, 0, v134
	v_max_f32_e32 v135, 0, v135
	v_pk_mul_f32 v[138:139], v[138:139], v[138:139]
	v_pk_mul_f32 v[140:141], v[140:141], v[140:141]
	v_pk_mul_f32 v[144:145], v[134:135], v[134:135]
	v_cvt_pk_f16_f32 v134, v138, v139
	v_cvt_pk_f16_f32 v135, v140, v141
	v_cvt_pk_f16_f32 v136, v142, v143
	v_cvt_pk_f16_f32 v137, v144, v145
	ds_read_b128 v[138:141], v129 offset:128
	ds_write_b128 v129, v[134:137] offset:48
	ds_read_b128 v[134:137], v129 offset:144
	s_waitcnt lgkmcnt(1)
	v_max_f32_e32 v138, v138, v138
	v_max_f32_e32 v139, v139, v139
	s_waitcnt lgkmcnt(0)
	v_max_f32_e32 v134, v134, v134
	v_max_f32_e32 v135, v135, v135
	v_max_f32_e32 v134, 0, v134
	v_max_f32_e32 v135, 0, v135
	v_max_f32_e32 v138, 0, v138
	v_max_f32_e32 v139, 0, v139
	v_pk_mul_f32 v[142:143], v[134:135], v[134:135]
	v_max_f32_e32 v134, v136, v136
	v_max_f32_e32 v135, v137, v137
	v_pk_mul_f32 v[138:139], v[138:139], v[138:139]
	v_max_f32_e32 v134, 0, v134
	v_max_f32_e32 v135, 0, v135
	v_pk_mul_f32 v[144:145], v[134:135], v[134:135]
	v_cvt_pk_f16_f32 v134, v138, v139
	v_add_u32_e32 v138, v133, v156
	v_max_f32_e32 v140, v140, v140
	v_max_f32_e32 v141, v141, v141
	v_ashrrev_i32_e32 v139, 31, v138
	v_max_f32_e32 v140, 0, v140
	v_max_f32_e32 v141, 0, v141
	v_cvt_pk_f16_f32 v136, v142, v143
	v_lshlrev_b64 v[142:143], 14, v[138:139]
	v_pk_mul_f32 v[140:141], v[140:141], v[140:141]
	v_lshl_add_u64 v[142:143], v[150:151], 0, v[142:143]
	v_cvt_pk_f16_f32 v135, v140, v141
	v_cvt_pk_f16_f32 v137, v144, v145
	v_lshl_add_u64 v[150:151], v[142:143], 0, v[152:153]
	ds_read_b128 v[138:141], v129 offset:160
	ds_write_b128 v129, v[134:137] offset:64
	ds_read_b128 v[134:137], v129 offset:176
	s_waitcnt lgkmcnt(1)
; DI unsigned pack2(float a, float b) { f32x2 v = {a, b}; bfx2 r = __builtin_convertvector(v, bfx2); return __builtin_bit_cast(unsigned, r); }
; DI size_t hid_off(int m, int c) { const int ml = m & 4095; return (size_t)(m >> 12) * (SLAB / 2) + ((size_t)((ml >> 8) * 128 + (c >> 5)) << 13) + (size_t)((ml & 255) * 32 + (c & 31)); }
; template <int MODE, bool BIG = false> DI void gemm_tile(const Params& p, int tm, int tn, int kv, char* smem) {
;     ...
;   } else if constexpr (MODE == G_FF1) {
;     u16* hid = (u16*)(p.ws + OFF_PROJ);
; #pragma unroll
;     for (int c8 = 0; c8 < 8; ++c8) {
;       float4 v0 = crow4[2 * c8], v1 = crow4[2 * c8 + 1];
;       float v[8] = {v0.x, v0.y, v0.z, v0.w, v1.x, v1.y, v1.z, v1.w};
; #pragma unroll
;       for (int e = 0; e < 8; ++e) { float t = fmaxf(v[e], 0.f); v[e] = t * t; }
;       *(uint4*)(hid + hid_off(m, col0 + c8 * 8)) = make_uint4(pack2(v[0], v[1]), pack2(v[2], v[3]), pack2(v[4], v[5]), pack2(v[6], v[7]));
;     }
	v_max_f32_e32 v138, v138, v138
	v_max_f32_e32 v139, v139, v139
	s_waitcnt lgkmcnt(0)
	v_max_f32_e32 v134, v134, v134
	v_max_f32_e32 v135, v135, v135
	v_max_f32_e32 v134, 0, v134
	v_max_f32_e32 v135, 0, v135
	v_max_f32_e32 v140, v140, v140
	v_max_f32_e32 v141, v141, v141
	v_pk_mul_f32 v[142:143], v[134:135], v[134:135]
	v_max_f32_e32 v134, v136, v136
	v_max_f32_e32 v135, v137, v137
	v_max_f32_e32 v138, 0, v138
	v_max_f32_e32 v139, 0, v139
	v_max_f32_e32 v140, 0, v140
	v_max_f32_e32 v141, 0, v141
	v_max_f32_e32 v134, 0, v134
	v_max_f32_e32 v135, 0, v135
	v_pk_mul_f32 v[138:139], v[138:139], v[138:139]
	v_pk_mul_f32 v[140:141], v[140:141], v[140:141]
	v_pk_mul_f32 v[144:145], v[134:135], v[134:135]
	v_cvt_pk_f16_f32 v134, v138, v139
	v_cvt_pk_f16_f32 v135, v140, v141
	v_cvt_pk_f16_f32 v136, v142, v143
	v_cvt_pk_f16_f32 v137, v144, v145
	ds_write_b128 v129, v[134:137] offset:80
	ds_read_b128 v[138:141], v129 offset:192
	ds_read_b128 v[134:137], v129 offset:208
	ds_read_b128 v[142:145], v129 offset:224
	ds_read_b128 v[146:149], v129 offset:240
	s_waitcnt lgkmcnt(2)
	v_max_f32_e32 v134, v134, v134
	v_max_f32_e32 v135, v135, v135
	v_max_f32_e32 v134, 0, v134
	v_max_f32_e32 v135, 0, v135
	v_max_f32_e32 v138, v138, v138
	v_max_f32_e32 v139, v139, v139
	v_max_f32_e32 v140, v140, v140
	v_max_f32_e32 v141, v141, v141
	v_pk_mul_f32 v[154:155], v[134:135], v[134:135]
	v_max_f32_e32 v134, v136, v136
	v_max_f32_e32 v135, v137, v137
	v_max_f32_e32 v138, 0, v138
	v_max_f32_e32 v139, 0, v139
	v_max_f32_e32 v140, 0, v140
	v_max_f32_e32 v141, 0, v141
	v_max_f32_e32 v134, 0, v134
	v_max_f32_e32 v135, 0, v135
	v_pk_mul_f32 v[138:139], v[138:139], v[138:139]
	v_pk_mul_f32 v[140:141], v[140:141], v[140:141]
	v_pk_mul_f32 v[156:157], v[134:135], v[134:135]
	v_cvt_pk_f16_f32 v134, v138, v139
	v_cvt_pk_f16_f32 v135, v140, v141
	v_cvt_pk_f16_f32 v136, v154, v155
	v_cvt_pk_f16_f32 v137, v156, v157
	ds_write_b128 v129, v[134:137] offset:96
	s_waitcnt lgkmcnt(0)
	v_max_f32_e32 v138, v146, v146
	v_max_f32_e32 v139, v147, v147
	v_max_f32_e32 v134, v142, v142
	v_max_f32_e32 v135, v143, v143
	v_max_f32_e32 v136, v144, v144
	v_max_f32_e32 v137, v145, v145
	v_max_f32_e32 v140, v148, v148
	v_max_f32_e32 v141, v149, v149
	v_max_f32_e32 v134, 0, v134
	v_max_f32_e32 v135, 0, v135
	v_max_f32_e32 v136, 0, v136
	v_max_f32_e32 v137, 0, v137
	v_max_f32_e32 v138, 0, v138
	v_max_f32_e32 v139, 0, v139
	v_max_f32_e32 v140, 0, v140
	v_max_f32_e32 v141, 0, v141
	v_pk_mul_f32 v[134:135], v[134:135], v[134:135]
	v_pk_mul_f32 v[136:137], v[136:137], v[136:137]
	v_pk_mul_f32 v[138:139], v[138:139], v[138:139]
	v_pk_mul_f32 v[140:141], v[140:141], v[140:141]
	v_cvt_pk_f16_f32 v134, v134, v135
	v_cvt_pk_f16_f32 v135, v136, v137
	v_cvt_pk_f16_f32 v136, v138, v139
	v_cvt_pk_f16_f32 v137, v140, v141
	ds_write_b128 v129, v[134:137] offset:112
	s_waitcnt lgkmcnt(0)
	s_barrier
	v_lshrrev_b32_e32 v152, 2, v173
	v_lshrrev_b32_e32 v156, 1, v173
	v_sub_u32_e32 v154, v152, v156
	v_lshlrev_b32_e32 v154, 6, v154
	v_and_b32_e32 v156, 1, v173
	v_lshl_add_u32 v156, v156, 1, 1
	v_lshlrev_b32_e32 v156, 14, v156
	v_sub_u32_e32 v154, v154, v156
	v_and_b32_e32 v156, 3, v173
	v_lshl_add_u32 v154, v156, 4, v154
	v_ashrrev_i32_e32 v155, 31, v154
	v_lshl_add_u64 v[154:155], v[150:151], 0, v[154:155]
	v_mul_u32_u24_e32 v152, 0x210, v152
	v_lshl_add_u32 v152, v156, 4, v152
	v_mov_b32_e32 v157, 0
	ds_read_b128 v[134:137], v152
	ds_read_b128 v[138:141], v152 offset:33792
	ds_read_b128 v[142:145], v152 offset:64
	ds_read_b128 v[146:149], v152 offset:33856
	s_waitcnt lgkmcnt(3)
	global_store_dwordx4 v[154:155], v[134:137], off
	v_mov_b32_e32 v156, 0x1000
	v_lshl_add_u64 v[154:155], v[156:157], 0, v[154:155]
	ds_read_b128 v[134:137], v152 offset:256
	s_waitcnt lgkmcnt(3)
	global_store_dwordx4 v[154:155], v[138:141], off
	v_mov_b32_e32 v156, 0x3000
	v_lshl_add_u64 v[154:155], v[156:157], 0, v[154:155]
	ds_read_b128 v[138:141], v152 offset:34048
	s_waitcnt lgkmcnt(3)
	global_store_dwordx4 v[154:155], v[142:145], off
	v_mov_b32_e32 v156, 0x1000
	v_lshl_add_u64 v[154:155], v[156:157], 0, v[154:155]
	ds_read_b128 v[142:145], v152 offset:320
	s_waitcnt lgkmcnt(3)
	global_store_dwordx4 v[154:155], v[146:149], off
	v_mov_b32_e32 v156, 0x3000
	v_lshl_add_u64 v[154:155], v[156:157], 0, v[154:155]
	ds_read_b128 v[146:149], v152 offset:34112
	s_waitcnt lgkmcnt(3)
	global_store_dwordx4 v[154:155], v[134:137], off
	v_mov_b32_e32 v156, 0x1000
	v_lshl_add_u64 v[154:155], v[156:157], 0, v[154:155]
	s_waitcnt lgkmcnt(2)
	global_store_dwordx4 v[154:155], v[138:141], off
	v_mov_b32_e32 v156, 0x3000
	v_lshl_add_u64 v[154:155], v[156:157], 0, v[154:155]
	s_waitcnt lgkmcnt(1)
	global_store_dwordx4 v[154:155], v[142:145], off
	v_mov_b32_e32 v156, 0x1000
	v_lshl_add_u64 v[154:155], v[156:157], 0, v[154:155]
	s_waitcnt lgkmcnt(0)
	global_store_dwordx4 v[154:155], v[146:149], off
	s_cbranch_vccz .LBB0_976
